# MLA attention loop: first eight transposed V reads of each PV block issued right after the last QK^T MFMA
# baseline (speedup 1.0000x reference)
; #define SBAR() __builtin_amdgcn_sched_barrier(0)
; template <int DQK, int DK1, int LDQ, int LDK, int LDKR, int LDV, int NQL, int SDEPTH>
; __device__ __forceinline__ void attn_core(const AttnArgs& a, char* lds, f32x16 (&o)[4]) {
;     ...
;         SBAR(); QKT(pB0, pB1, K_lds + SHM_K);
;         finishSM(pA0, pA1, alA, l_reg, pa0, pa1, pa2, pa3); SBAR();
.LBB0_219:
	ds_read_b128 v[64:67], v184 offset:57344
	ds_read_b128 v[68:71], v216 offset:12288
	ds_read_b128 v[222:225], v192 offset:57344
	ds_read_b128 v[226:229], v208 offset:12288
	v_exp_f32_e32 v207, v130
	v_add_f32_e32 v130, 0, v219
	s_waitcnt lgkmcnt(3)
	v_mfma_f32_32x32x16_bf16 v[80:95], v[64:67], v[126:129], 0
	v_add_f32_e32 v130, v221, v130
	v_add_f32_e32 v130, v157, v130
	v_add_f32_e32 v130, v220, v130
	v_add_f32_e32 v130, v156, v130
	v_add_f32_e32 v130, v218, v130
	v_add_f32_e32 v130, v154, v130
	v_add_f32_e32 v130, v155, v130
	s_waitcnt lgkmcnt(2)
	v_mfma_f32_32x32x16_bf16 v[64:79], v[68:71], v[126:129], 0
	v_add_f32_e32 v130, v151, v130
	v_add_f32_e32 v130, v153, v130
	v_add_f32_e32 v130, v150, v130
	v_add_f32_e32 v130, v152, v130
	v_exp_f32_e32 v142, v142
	v_add_f32_e32 v130, v147, v130
	v_exp_f32_e32 v143, v143
	s_waitcnt lgkmcnt(1)
	v_mfma_f32_32x32x16_bf16 v[80:95], v[222:225], v[122:125], v[80:95]
	v_add_f32_e32 v130, v149, v130
	v_exp_f32_e32 v140, v140
	v_add_f32_e32 v130, v146, v130
	v_exp_f32_e32 v141, v141
	v_add_f32_e32 v130, v148, v130
	v_exp_f32_e32 v134, v134
	v_add_f32_e32 v130, v142, v130
	s_waitcnt lgkmcnt(0)
	v_mfma_f32_32x32x16_bf16 v[64:79], v[226:229], v[122:125], v[64:79]
	ds_read_b128 v[222:225], v190 offset:57344
	ds_read_b128 v[226:229], v206 offset:12288
	v_exp_f32_e32 v135, v135
	v_add_f32_e32 v130, v143, v130
	v_exp_f32_e32 v191, v132
	v_add_f32_e32 v130, v140, v130
	v_exp_f32_e32 v205, v133
	v_add_f32_e32 v130, v141, v130
	s_waitcnt lgkmcnt(1)
	v_mfma_f32_32x32x16_bf16 v[80:95], v[222:225], v[118:121], v[80:95]
	v_add_f32_e32 v130, v134, v130
	v_exp_f32_e32 v210, v131
	v_add_f32_e32 v130, v135, v130
	v_exp_f32_e32 v144, v144
	v_add_f32_e32 v130, v191, v130
	v_exp_f32_e32 v145, v145
	v_add_f32_e32 v130, v205, v130
	s_waitcnt lgkmcnt(0)
	v_mfma_f32_32x32x16_bf16 v[64:79], v[226:229], v[118:121], v[64:79]
	ds_read_b128 v[222:225], v173 offset:57344
	ds_read_b128 v[226:229], v202 offset:12288
	v_exp_f32_e32 v138, v138
	v_add_f32_e32 v130, v207, v130
	v_exp_f32_e32 v139, v139
	v_add_f32_e32 v130, v210, v130
	v_exp_f32_e32 v136, v136
	v_add_f32_e32 v130, v144, v130
	s_waitcnt lgkmcnt(1)
	v_mfma_f32_32x32x16_bf16 v[80:95], v[222:225], v[114:117], v[80:95]
	v_exp_f32_e32 v137, v137
	v_add_f32_e32 v130, v145, v130
	v_add_f32_e32 v130, v138, v130
	v_add_f32_e32 v130, v139, v130
	v_add_f32_e32 v130, v136, v130
	s_waitcnt lgkmcnt(0)
	v_mfma_f32_32x32x16_bf16 v[64:79], v[226:229], v[114:117], v[64:79]
	ds_read_b128 v[222:225], v184 offset:57472
	ds_read_b128 v[226:229], v216 offset:12416
	s_waitcnt lgkmcnt(1)
	v_mfma_f32_32x32x16_bf16 v[80:95], v[222:225], v[110:113], v[80:95]
	s_waitcnt lgkmcnt(0)
	v_mfma_f32_32x32x16_bf16 v[64:79], v[226:229], v[110:113], v[64:79]
	ds_read_b128 v[222:225], v192 offset:57472
	ds_read_b128 v[226:229], v208 offset:12416
	s_waitcnt lgkmcnt(1)
	v_mfma_f32_32x32x16_bf16 v[80:95], v[222:225], v[106:109], v[80:95]
	s_waitcnt lgkmcnt(0)
	v_mfma_f32_32x32x16_bf16 v[64:79], v[226:229], v[106:109], v[64:79]
	ds_read_b128 v[222:225], v190 offset:57472
	ds_read_b128 v[226:229], v206 offset:12416
	s_waitcnt lgkmcnt(1)
	v_mfma_f32_32x32x16_bf16 v[80:95], v[222:225], v[102:105], v[80:95]
	s_waitcnt lgkmcnt(0)
	v_mfma_f32_32x32x16_bf16 v[64:79], v[226:229], v[102:105], v[64:79]
	ds_read_b128 v[222:225], v173 offset:57472
	ds_read_b128 v[226:229], v202 offset:12416
	s_waitcnt lgkmcnt(1)
	v_mfma_f32_32x32x16_bf16 v[80:95], v[222:225], v[98:101], v[80:95]
	s_waitcnt lgkmcnt(0)
	v_mfma_f32_32x32x16_bf16 v[64:79], v[226:229], v[98:101], v[64:79]
	ds_read_b128 v[222:225], v184 offset:57600
	ds_read_b128 v[226:229], v216 offset:12544
	ds_read_b128 v[230:233], v181
	s_waitcnt lgkmcnt(0)
	v_mfma_f32_32x32x16_bf16 v[80:95], v[222:225], v[230:233], v[80:95]
	v_mfma_f32_32x32x16_bf16 v[64:79], v[226:229], v[230:233], v[64:79]
	ds_read_b128 v[222:225], v192 offset:57600
	ds_read_b128 v[226:229], v208 offset:12544
	ds_read_b128 v[230:233], v181 offset:8192
	s_waitcnt lgkmcnt(0)
	v_mfma_f32_32x32x16_bf16 v[80:95], v[222:225], v[230:233], v[80:95]
	v_mfma_f32_32x32x16_bf16 v[64:79], v[226:229], v[230:233], v[64:79]
	ds_read_b128 v[222:225], v190 offset:57600
	ds_read_b128 v[226:229], v206 offset:12544
	ds_read_b128 v[230:233], v181 offset:16384
	s_waitcnt lgkmcnt(0)
	v_mfma_f32_32x32x16_bf16 v[80:95], v[222:225], v[230:233], v[80:95]
	v_mfma_f32_32x32x16_bf16 v[64:79], v[226:229], v[230:233], v[64:79]
	ds_read_b128 v[222:225], v173 offset:57600
	ds_read_b128 v[226:229], v202 offset:12544
	ds_read_b128 v[230:233], v181 offset:24576
	s_waitcnt lgkmcnt(0)
; template <int D0> __device__ __forceinline__ void pv_one(f32x16& od, int vb, bf16x8 pa0, bf16x8 pa1, bf16x8 pa2, bf16x8 pa3) {
;     const s16x4 l0 = tr_read<v_rd_off(D0, 0, 0)>(vb), h0 = tr_read<v_rd_off(D0, 0, 1)>(vb), l1 = tr_read<v_rd_off(D0, 1, 0)>(vb), h1 = tr_read<v_rd_off(D0, 1, 1)>(vb);
;     const s16x4 l2 = tr_read<v_rd_off(D0, 2, 0)>(vb), h2 = tr_read<v_rd_off(D0, 2, 1)>(vb), l3 = tr_read<v_rd_off(D0, 3, 0)>(vb), h3 = tr_read<v_rd_off(D0, 3, 1)>(vb);
;     asm volatile("s_waitcnt lgkmcnt(0)" ::: "memory"); SBAR();
;     ...
;     od = __builtin_amdgcn_mfma_f32_32x32x16_bf16(pa0, PK(l0, h0), od, 0, 0, 0);
;     od = __builtin_amdgcn_mfma_f32_32x32x16_bf16(pa1, PK(l1, h1), od, 0, 0, 0);
;     od = __builtin_amdgcn_mfma_f32_32x32x16_bf16(pa2, PK(l2, h2), od, 0, 0, 0);
;     od = __builtin_amdgcn_mfma_f32_32x32x16_bf16(pa3, PK(l3, h3), od, 0, 0, 0);
;     ...
; }
; __device__ __forceinline__ void pv_d0(f32x16* o, int vb, bf16x8 pa0, bf16x8 pa1, bf16x8 pa2, bf16x8 pa3) {
;     pv_one<0>(o[0], vb, pa0, pa1, pa2, pa3); pv_one<1>(o[1], vb, pa0, pa1, pa2, pa3); pv_one<2>(o[2], vb, pa0, pa1, pa2, pa3); pv_one<3>(o[3], vb, pa0, pa1, pa2, pa3);
; }
; __device__ __forceinline__ void partialSM(f32x16& p0, f32x16& p1, float& m_reg, float& mn, float& alpha, const float C, const float thr) {
;     float pmax = p0[0];
; #pragma unroll
;     for (int r = 1; r < 16; ++r) pmax = fmaxf(pmax, p0[r]);
; #pragma unroll
;     for (int r = 0; r < 16; ++r) pmax = fmaxf(pmax, p1[r]);
;     { auto rr = __builtin_amdgcn_permlane32_swap(__float_as_uint(pmax), __float_as_uint(pmax), false, false);
;       pmax = fmaxf(__uint_as_float(rr[0]), __uint_as_float(rr[1])); }
;     if (__builtin_expect(__all(pmax - m_reg <= thr), 1)) { mn = m_reg; alpha = 1.f; }
;     else { mn = fmaxf(m_reg, pmax); alpha = __builtin_amdgcn_exp2f((m_reg - mn) * C); m_reg = mn; }
;     const float mnC = -mn * C;
; #pragma unroll
;     for (int r = 0; r < 16; ++r) p0[r] = fmaf(p0[r], C, mnC);
; #pragma unroll
;     for (int r = 0; r < 16; ++r) p1[r] = fmaf(p1[r], C, mnC);
; #pragma unroll
;     for (int r = 0; r < 16; ++r) p0[r] = __builtin_amdgcn_exp2f(p0[r]);
; }
; __device__ __forceinline__ void finishSM(f32x16& p0, f32x16& p1, float alpha, float& l_reg, bf16x8& pa0, bf16x8& pa1, bf16x8& pa2, bf16x8& pa3) {
; #pragma unroll
;     for (int r = 0; r < 16; ++r) p1[r] = __builtin_amdgcn_exp2f(p1[r]);
;     float ps = 0;
	v_mfma_f32_32x32x16_bf16 v[80:95], v[222:225], v[230:233], v[80:95]
	v_add_f32_e32 v222, v137, v130
	v_mov_b32_e32 v223, v222
	v_cvt_pk_bf16_f32 v130, v219, v221
	v_cvt_pk_bf16_f32 v131, v157, v220
	v_cvt_pk_bf16_f32 v132, v156, v218
	v_cvt_pk_bf16_f32 v133, v154, v155
	v_cvt_pk_bf16_f32 v154, v151, v153
	v_mfma_f32_32x32x16_bf16 v[64:79], v[226:229], v[230:233], v[64:79]
	ds_read_b64_tr_b16 v[228:229], v200 offset:0
	ds_read_b64_tr_b16 v[230:231], v200 offset:0x800
	ds_read_b64_tr_b16 v[232:233], v200 offset:0x1000
	ds_read_b64_tr_b16 v[234:235], v200 offset:0x1800
	ds_read_b64_tr_b16 v[236:237], v200 offset:0x2000
	ds_read_b64_tr_b16 v[238:239], v200 offset:0x2800
	ds_read_b64_tr_b16 v[240:241], v200 offset:0x3000
	ds_read_b64_tr_b16 v[242:243], v200 offset:0x3800
	v_cvt_pk_bf16_f32 v155, v150, v152
	v_cvt_pk_bf16_f32 v156, v147, v149
	v_cvt_pk_bf16_f32 v157, v146, v148
	v_cvt_pk_bf16_f32 v218, v142, v143
	v_cvt_pk_bf16_f32 v219, v140, v141
	v_cvt_pk_bf16_f32 v220, v134, v135
	v_cvt_pk_bf16_f32 v221, v191, v205
	v_cvt_pk_bf16_f32 v224, v207, v210
	v_cvt_pk_bf16_f32 v225, v144, v145
	v_cvt_pk_bf16_f32 v226, v138, v139
	v_cvt_pk_bf16_f32 v227, v136, v137
	s_nop 0
	v_permlane32_swap_b32_e32 v222, v223
	v_permlane32_swap_b32_e32 v130, v132
	v_permlane32_swap_b32_e32 v225, v227
	v_permlane32_swap_b32_e32 v131, v133
	v_permlane32_swap_b32_e32 v154, v156
	v_permlane32_swap_b32_e32 v155, v157
	v_permlane32_swap_b32_e32 v218, v220
	v_permlane32_swap_b32_e32 v219, v221
	v_permlane32_swap_b32_e32 v224, v226
	s_cmp_lt_u32 s69, s68
	s_cselect_b32 s14, 0, s68
	s_cselect_b32 s15, s25, s28
	s_lshl_b32 s14, s14, 6
	s_sub_i32 s14, s15, s14
	s_add_i32 s14, s37, s14
	s_ashr_i32 s15, s14, 31
	v_lshl_add_u64 v[134:135], s[14:15], 0, v[174:175]
	v_lshl_add_u64 v[136:137], v[176:177], 0, s[14:15]
	v_lshlrev_b64 v[134:135], 12, v[134:135]
	v_lshlrev_b64 v[136:137], 12, v[136:137]
	v_lshl_add_u64 v[134:135], v[178:179], 0, v[134:135]
	v_lshl_add_u64 v[138:139], v[178:179], 0, v[136:137]
	v_mad_i64_i32 v[142:143], s[20:21], v164, s14, 0
	v_mad_i64_i32 v[146:147], s[20:21], v168, s14, 0
	v_mad_i64_i32 v[150:151], s[14:15], v172, s14, 0
	global_load_dwordx4 v[134:137], v[134:135], off offset:256
	s_nop 0
	global_load_dwordx4 v[138:141], v[138:139], off offset:256
	v_lshl_add_u64 v[142:143], v[142:143], 1, v[162:163]
	v_lshl_add_u64 v[146:147], v[146:147], 1, v[166:167]
	v_lshl_add_u64 v[150:151], v[150:151], 1, v[170:171]
	global_load_dwordx4 v[142:145], v[142:143], off
	s_nop 0
	global_load_dwordx4 v[146:149], v[146:147], off
	s_nop 0
	global_load_dwordx4 v[150:153], v[150:151], off
	s_waitcnt lgkmcnt(0)
	s_nop 0
	v_mfma_f32_32x32x16_bf16 v[48:63], v[130:133], v[228:231], v[48:63]
	ds_read_b64_tr_b16 v[228:229], v200 offset:0x200
	ds_read_b64_tr_b16 v[230:231], v200 offset:0xa00
	v_mfma_f32_32x32x16_bf16 v[48:63], v[154:157], v[232:235], v[48:63]
	ds_read_b64_tr_b16 v[232:233], v200 offset:0x1200
	ds_read_b64_tr_b16 v[234:235], v200 offset:0x1a00
	v_mfma_f32_32x32x16_bf16 v[48:63], v[218:221], v[236:239], v[48:63]
	ds_read_b64_tr_b16 v[236:237], v200 offset:0x2200
	ds_read_b64_tr_b16 v[238:239], v200 offset:0x2a00
	v_mfma_f32_32x32x16_bf16 v[48:63], v[224:227], v[240:243], v[48:63]
	ds_read_b64_tr_b16 v[240:241], v200 offset:0x3200
	ds_read_b64_tr_b16 v[242:243], v200 offset:0x3a00
	s_waitcnt lgkmcnt(0)
	v_mfma_f32_32x32x16_bf16 v[32:47], v[130:133], v[228:231], v[32:47]
	ds_read_b64_tr_b16 v[228:229], v200 offset:0x400
	ds_read_b64_tr_b16 v[230:231], v200 offset:0xc00
	v_mfma_f32_32x32x16_bf16 v[32:47], v[154:157], v[232:235], v[32:47]
	ds_read_b64_tr_b16 v[232:233], v200 offset:0x1400
	ds_read_b64_tr_b16 v[234:235], v200 offset:0x1c00
	v_mfma_f32_32x32x16_bf16 v[32:47], v[218:221], v[236:239], v[32:47]
	ds_read_b64_tr_b16 v[236:237], v200 offset:0x2400
	ds_read_b64_tr_b16 v[238:239], v200 offset:0x2c00
	v_mfma_f32_32x32x16_bf16 v[32:47], v[224:227], v[240:243], v[32:47]
	ds_read_b64_tr_b16 v[240:241], v200 offset:0x3400
	ds_read_b64_tr_b16 v[242:243], v200 offset:0x3c00
	s_waitcnt lgkmcnt(0)
	v_mfma_f32_32x32x16_bf16 v[16:31], v[130:133], v[228:231], v[16:31]
	ds_read_b64_tr_b16 v[228:229], v200 offset:0x600
	ds_read_b64_tr_b16 v[230:231], v200 offset:0xe00
	v_mfma_f32_32x32x16_bf16 v[16:31], v[154:157], v[232:235], v[16:31]
	ds_read_b64_tr_b16 v[232:233], v200 offset:0x1600
	ds_read_b64_tr_b16 v[234:235], v200 offset:0x1e00
	v_mfma_f32_32x32x16_bf16 v[16:31], v[218:221], v[236:239], v[16:31]
	ds_read_b64_tr_b16 v[236:237], v200 offset:0x2600
	ds_read_b64_tr_b16 v[238:239], v200 offset:0x2e00
	v_mfma_f32_32x32x16_bf16 v[16:31], v[224:227], v[240:243], v[16:31]
	ds_read_b64_tr_b16 v[240:241], v200 offset:0x3600
	ds_read_b64_tr_b16 v[242:243], v200 offset:0x3e00
	s_waitcnt lgkmcnt(0)
	v_mfma_f32_32x32x16_bf16 v[0:15], v[130:133], v[228:231], v[0:15]
	v_max_f32_e32 v130, v81, v81
	v_max_f32_e32 v131, v80, v80
	v_max_f32_e32 v130, v131, v130
	v_max3_f32 v130, v130, v82, v83
	v_max3_f32 v130, v130, v84, v85
	v_max3_f32 v130, v130, v86, v87
	v_max3_f32 v130, v130, v88, v89
	v_max3_f32 v130, v130, v90, v91
	v_max3_f32 v130, v130, v92, v93
	v_mfma_f32_32x32x16_bf16 v[0:15], v[154:157], v[232:235], v[0:15]
	v_max3_f32 v130, v130, v94, v95
	v_max3_f32 v130, v130, v64, v65
	v_max3_f32 v130, v130, v66, v67
	v_max3_f32 v130, v130, v68, v69
	v_max3_f32 v130, v130, v70, v71
	v_max3_f32 v130, v130, v72, v73
	v_max3_f32 v130, v130, v74, v75
	v_max3_f32 v130, v130, v76, v77
	v_mfma_f32_32x32x16_bf16 v[0:15], v[218:221], v[236:239], v[0:15]
	v_max3_f32 v130, v130, v78, v79
	v_mov_b32_e32 v131, v130
	s_nop 1
	v_permlane32_swap_b32_e32 v130, v131
	v_max_f32_e32 v131, v131, v131
	v_max_f32_e32 v130, v130, v130
	v_max_f32_e32 v130, v130, v131
	v_sub_f32_e32 v131, v130, v204
	v_cmp_ge_f32_e32 vcc, s72, v131
	v_max_f32_e32 v131, v204, v204
	v_max_f32_e32 v130, v131, v130
	v_mfma_f32_32x32x16_bf16 v[0:15], v[224:227], v[240:243], v[0:15]
	v_sub_f32_e32 v131, v204, v130
	v_mul_f32_e32 v131, 0x3dd53b94, v131
	v_exp_f32_e32 v131, v131
	s_cmp_eq_u64 vcc, exec
	s_cselect_b64 s[14:15], -1, 0
	v_cndmask_b32_e64 v225, v131, 1.0, s[14:15]
	v_cmp_gt_f32_e32 vcc, 1.0, v225
	s_barrier
; #define SBAR() __builtin_amdgcn_sched_barrier(0)
; #define SWRITE(b, i) do { *(bf16x8*)(V_lds + (b) * SHM_V + vst0) = sr_[i].vs0; *(bf16x8*)(V_lds + (b) * SHM_V + vst1) = sr_[i].vs1; \
;     _Pragma("unroll") for (int c_ = 0; c_ < KCH; ++c_) *(bf16x8*)(K_lds + (b) * SHM_K + kwo[c_]) = sr_[i].ks[c_]; } while (0)
; #define RESC(al) do { if (__any((al) < 1.f)) { if (hi == 0) al_l[r32] = (al); asm volatile("s_waitcnt lgkmcnt(0)" ::: "memory"); \
;     _Pragma("unroll") for (int d = 0; d < 4; ++d) _Pragma("unroll") for (int r = 0; r < 16; ++r) o[d][r] *= al_l[crow(r, hi)]; } } while (0)
; __device__ __forceinline__ void partialSM(f32x16& p0, f32x16& p1, float& m_reg, float& mn, float& alpha, const float C, const float thr) {
;     ...
;     const float mnC = -mn * C;
; #pragma unroll
;     for (int r = 0; r < 16; ++r) p0[r] = fmaf(p0[r], C, mnC);
; #pragma unroll
;     for (int r = 0; r < 16; ++r) p1[r] = fmaf(p1[r], C, mnC);
; #pragma unroll
;     for (int r = 0; r < 16; ++r) p0[r] = __builtin_amdgcn_exp2f(p0[r]);
; }
; __device__ __forceinline__ void finishSM(f32x16& p0, f32x16& p1, float alpha, float& l_reg, bf16x8& pa0, bf16x8& pa1, bf16x8& pa2, bf16x8& pa3) {
; #pragma unroll
;     for (int r = 0; r < 16; ++r) p1[r] = __builtin_amdgcn_exp2f(p1[r]);
; template <int DQK, int DK1, int LDQ, int LDK, int LDKR, int LDV, int NQL, int SDEPTH>
; __device__ __forceinline__ void attn_core(const AttnArgs& a, char* lds, f32x16 (&o)[4]) {
;     ...
;         __syncthreads(); SWRITE(0, SE);
;         RESC(alB); __syncthreads();
;         SBAR(); QKT(pA0, pA1, K_lds);
	s_waitcnt vmcnt(4)
	ds_write_b128 v186, v[134:137]
	s_waitcnt vmcnt(3)
	ds_write_b128 v188, v[138:141]
	s_waitcnt vmcnt(2)
	ds_write_b128 v194, v[142:145] offset:32768
	s_waitcnt vmcnt(1)
	ds_write_b128 v196, v[146:149] offset:32768
	s_waitcnt vmcnt(0)
	ds_write_b128 v198, v[150:153] offset:32768
	s_cbranch_vccz .LBB0_223
	s_and_saveexec_b64 s[20:21], s[12:13]
	ds_write_b32 v165, v225 offset:128
	s_or_b64 exec, exec, s[20:21]
	s_waitcnt lgkmcnt(0)
	v_add_u32_e32 v131, v161, v96
	ds_read_b128 v[132:135], v131 offset:224
	ds_read_b128 v[136:139], v131 offset:192
	ds_read_b128 v[140:143], v131 offset:160
	ds_read_b128 v[144:147], v131 offset:128
	s_waitcnt lgkmcnt(3)
	v_pk_mul_f32 v[60:61], v[60:61], v[132:133]
	s_waitcnt lgkmcnt(2)
	v_pk_mul_f32 v[56:57], v[56:57], v[136:137]
	s_waitcnt lgkmcnt(1)
	v_pk_mul_f32 v[52:53], v[52:53], v[140:141]
	v_pk_mul_f32 v[62:63], v[62:63], v[134:135]
	v_pk_mul_f32 v[58:59], v[58:59], v[138:139]
	v_pk_mul_f32 v[54:55], v[54:55], v[142:143]
	s_waitcnt lgkmcnt(0)
	v_pk_mul_f32 v[50:51], v[50:51], v[146:147]
	v_pk_mul_f32 v[48:49], v[48:49], v[144:145]
	v_pk_mul_f32 v[44:45], v[44:45], v[132:133]
	v_pk_mul_f32 v[40:41], v[40:41], v[136:137]
	v_pk_mul_f32 v[36:37], v[36:37], v[140:141]
	v_pk_mul_f32 v[46:47], v[46:47], v[134:135]
	v_pk_mul_f32 v[42:43], v[42:43], v[138:139]
	v_pk_mul_f32 v[38:39], v[38:39], v[142:143]
	v_pk_mul_f32 v[34:35], v[34:35], v[146:147]
	v_pk_mul_f32 v[32:33], v[32:33], v[144:145]
	v_pk_mul_f32 v[28:29], v[28:29], v[132:133]
	v_pk_mul_f32 v[24:25], v[24:25], v[136:137]
	v_pk_mul_f32 v[20:21], v[20:21], v[140:141]
	v_pk_mul_f32 v[30:31], v[30:31], v[134:135]
	v_pk_mul_f32 v[26:27], v[26:27], v[138:139]
	v_pk_mul_f32 v[22:23], v[22:23], v[142:143]
	v_pk_mul_f32 v[18:19], v[18:19], v[146:147]
	v_pk_mul_f32 v[16:17], v[16:17], v[144:145]
	v_pk_mul_f32 v[12:13], v[12:13], v[132:133]
	v_pk_mul_f32 v[8:9], v[8:9], v[136:137]
	v_pk_mul_f32 v[4:5], v[4:5], v[140:141]
	v_pk_mul_f32 v[14:15], v[14:15], v[134:135]
	v_pk_mul_f32 v[10:11], v[10:11], v[138:139]
	v_pk_mul_f32 v[6:7], v[6:7], v[142:143]
	v_pk_mul_f32 v[2:3], v[2:3], v[146:147]
	v_pk_mul_f32 v[0:1], v[0:1], v[144:145]
.LBB0_223:
	v_cndmask_b32_e64 v204, v130, v204, s[14:15]
	v_mul_f32_e32 v138, 0xbdd53b94, v204
	v_fmamk_f32 v80, v80, 0x3dd53b94, v138
	v_fmamk_f32 v140, v70, 0x3dd53b94, v138
	v_fmamk_f32 v70, v87, 0x3dd53b94, v138
	v_exp_f32_e32 v130, v80
	v_exp_f32_e32 v224, v70
	v_fmamk_f32 v82, v82, 0x3dd53b94, v138
	v_fmamk_f32 v84, v84, 0x3dd53b94, v138
	v_fmamk_f32 v86, v86, 0x3dd53b94, v138
	v_fmamk_f32 v88, v88, 0x3dd53b94, v138
	v_fmamk_f32 v90, v90, 0x3dd53b94, v138
	v_fmamk_f32 v92, v92, 0x3dd53b94, v138
	v_fmamk_f32 v94, v94, 0x3dd53b94, v138
	v_fmamk_f32 v145, v64, 0x3dd53b94, v138
	v_fmamk_f32 v144, v66, 0x3dd53b94, v138
	v_fmamk_f32 v143, v68, 0x3dd53b94, v138
	v_fmamk_f32 v139, v72, 0x3dd53b94, v138
	v_fmamk_f32 v146, v74, 0x3dd53b94, v138
	v_fmamk_f32 v142, v76, 0x3dd53b94, v138
	v_fmamk_f32 v141, v78, 0x3dd53b94, v138
	v_fmamk_f32 v64, v81, 0x3dd53b94, v138
	v_fmamk_f32 v66, v83, 0x3dd53b94, v138
	v_fmamk_f32 v68, v85, 0x3dd53b94, v138
	v_fmamk_f32 v72, v89, 0x3dd53b94, v138
	v_fmamk_f32 v74, v91, 0x3dd53b94, v138
	v_fmamk_f32 v76, v93, 0x3dd53b94, v138
	v_fmamk_f32 v78, v95, 0x3dd53b94, v138
	v_exp_f32_e32 v131, v82
	v_exp_f32_e32 v132, v84
	v_exp_f32_e32 v133, v86
	v_exp_f32_e32 v137, v88
	v_exp_f32_e32 v136, v90
	v_exp_f32_e32 v135, v92
	v_exp_f32_e32 v134, v94
	v_fmamk_f32 v147, v65, 0x3dd53b94, v138
	v_fmamk_f32 v156, v67, 0x3dd53b94, v138
	v_fmamk_f32 v157, v69, 0x3dd53b94, v138
	v_fmamk_f32 v191, v71, 0x3dd53b94, v138
	v_fmamk_f32 v205, v73, 0x3dd53b94, v138
	v_fmamk_f32 v207, v75, 0x3dd53b94, v138
	v_fmamk_f32 v210, v77, 0x3dd53b94, v138
	v_fmac_f32_e32 v138, 0x3dd53b94, v79
	v_exp_f32_e32 v211, v64
	v_exp_f32_e32 v212, v66
	v_exp_f32_e32 v213, v68
	v_exp_f32_e32 v228, v72
	v_exp_f32_e32 v229, v74
	v_exp_f32_e32 v230, v76
	v_exp_f32_e32 v231, v78
	s_waitcnt lgkmcnt(0)
	s_barrier
	ds_read_b128 v[64:67], v184 offset:32768
	ds_read_b128 v[68:71], v184 offset:45056
	ds_read_b128 v[148:151], v192 offset:32768
	ds_read_b128 v[152:155], v192 offset:45056
	v_exp_f32_e32 v145, v145
	v_exp_f32_e32 v147, v147
	s_waitcnt lgkmcnt(3)
	v_mfma_f32_32x32x16_bf16 v[80:95], v[64:67], v[126:129], 0
	v_exp_f32_e32 v144, v144
	v_exp_f32_e32 v143, v143
	v_exp_f32_e32 v140, v140
	v_exp_f32_e32 v139, v139
	v_exp_f32_e32 v146, v146
	v_exp_f32_e32 v142, v142
	v_exp_f32_e32 v141, v141
	s_waitcnt lgkmcnt(2)
	v_mfma_f32_32x32x16_bf16 v[64:79], v[68:71], v[126:129], 0
	v_exp_f32_e32 v138, v138
	s_waitcnt lgkmcnt(0)
	v_mfma_f32_32x32x16_bf16 v[64:79], v[152:155], v[122:125], v[64:79]
	v_mfma_f32_32x32x16_bf16 v[80:95], v[148:151], v[122:125], v[80:95]
	ds_read_b128 v[148:151], v190 offset:32768
	ds_read_b128 v[152:155], v190 offset:45056
	s_waitcnt lgkmcnt(0)
	v_mfma_f32_32x32x16_bf16 v[64:79], v[152:155], v[118:121], v[64:79]
	v_mfma_f32_32x32x16_bf16 v[80:95], v[148:151], v[118:121], v[80:95]
	ds_read_b128 v[148:151], v173 offset:32768
	ds_read_b128 v[152:155], v173 offset:45056
	s_waitcnt lgkmcnt(0)
	v_mfma_f32_32x32x16_bf16 v[64:79], v[152:155], v[114:117], v[64:79]
	v_mfma_f32_32x32x16_bf16 v[80:95], v[148:151], v[114:117], v[80:95]
	ds_read_b128 v[148:151], v184 offset:32896
	ds_read_b128 v[152:155], v184 offset:45184
	s_waitcnt lgkmcnt(0)
	v_mfma_f32_32x32x16_bf16 v[64:79], v[152:155], v[110:113], v[64:79]
	v_mfma_f32_32x32x16_bf16 v[80:95], v[148:151], v[110:113], v[80:95]
	ds_read_b128 v[148:151], v192 offset:32896
	ds_read_b128 v[152:155], v192 offset:45184
	s_waitcnt lgkmcnt(0)
; #define SBAR() __builtin_amdgcn_sched_barrier(0)
; #define SLOAD(i, j) do { const long rb_ = KROW(j); sr_[i].vs0 = *(const bf16x8*)(a.V + (rb_ + sr) * LDV + sc); sr_[i].vs1 = *(const bf16x8*)(a.V + (rb_ + 32 + sr) * LDV + sc); \
;     _Pragma("unroll") for (int c_ = 0; c_ < KCH; ++c_) sr_[i].ks[c_] = *(const bf16x8*)(kptr[c_] + rb_ * kld[c_]); } while (0)
; __device__ __forceinline__ void finishSM(f32x16& p0, f32x16& p1, float alpha, float& l_reg, bf16x8& pa0, bf16x8& pa1, bf16x8& pa2, bf16x8& pa3) {
; #pragma unroll
;     for (int r = 0; r < 16; ++r) p1[r] = __builtin_amdgcn_exp2f(p1[r]);
;     float ps = 0;
; #pragma unroll
;     for (int r = 0; r < 16; ++r) ps += p0[r];
; #pragma unroll
;     for (int r = 0; r < 16; ++r) ps += p1[r];
;     { auto rr = __builtin_amdgcn_permlane32_swap(__float_as_uint(ps), __float_as_uint(ps), false, false);
;       ps = __uint_as_float(rr[0]) + __uint_as_float(rr[1]); }
;     l_reg = l_reg * alpha + ps;
;     ...
;     PK4(p0, 0, pa0); PK4(p0, 8, pa1); PK4(p1, 0, pa2); PK4(p1, 8, pa3);
;     ...
; }
; template <int DQK, int DK1, int LDQ, int LDK, int LDKR, int LDV, int NQL, int SDEPTH>
; __device__ __forceinline__ void attn_core(const AttnArgs& a, char* lds, f32x16 (&o)[4]) {
;     ...
;         SBAR(); QKT(pA0, pA1, K_lds);
;         finishSM(pB0, pB1, alB, l_reg, pa0, pa1, pa2, pa3); SBAR();
;         if (SDEPTH == 1 || j + 3 < NT) SLOAD(SE, j + 1 + SDEPTH); SBAR();
	v_mfma_f32_32x32x16_bf16 v[64:79], v[152:155], v[106:109], v[64:79]
	v_mfma_f32_32x32x16_bf16 v[80:95], v[148:151], v[106:109], v[80:95]
	ds_read_b128 v[148:151], v190 offset:32896
	ds_read_b128 v[152:155], v190 offset:45184
	s_waitcnt lgkmcnt(0)
	v_mfma_f32_32x32x16_bf16 v[64:79], v[152:155], v[102:105], v[64:79]
	v_mfma_f32_32x32x16_bf16 v[80:95], v[148:151], v[102:105], v[80:95]
	ds_read_b128 v[148:151], v173 offset:32896
	ds_read_b128 v[152:155], v173 offset:45184
	s_waitcnt lgkmcnt(0)
	v_mfma_f32_32x32x16_bf16 v[64:79], v[152:155], v[98:101], v[64:79]
	v_mfma_f32_32x32x16_bf16 v[80:95], v[148:151], v[98:101], v[80:95]
	ds_read_b128 v[148:151], v184 offset:33024
	ds_read_b128 v[152:155], v184 offset:45312
	ds_read_b128 v[218:221], v181
	s_waitcnt lgkmcnt(0)
	v_mfma_f32_32x32x16_bf16 v[64:79], v[152:155], v[218:221], v[64:79]
	v_mfma_f32_32x32x16_bf16 v[80:95], v[148:151], v[218:221], v[80:95]
	ds_read_b128 v[148:151], v192 offset:33024
	ds_read_b128 v[152:155], v192 offset:45312
	ds_read_b128 v[218:221], v181 offset:8192
	s_waitcnt lgkmcnt(0)
	v_mfma_f32_32x32x16_bf16 v[64:79], v[152:155], v[218:221], v[64:79]
	v_mfma_f32_32x32x16_bf16 v[80:95], v[148:151], v[218:221], v[80:95]
	ds_read_b128 v[148:151], v190 offset:33024
	ds_read_b128 v[152:155], v190 offset:45312
	ds_read_b128 v[218:221], v181 offset:16384
	s_waitcnt lgkmcnt(0)
	v_mfma_f32_32x32x16_bf16 v[64:79], v[152:155], v[218:221], v[64:79]
	v_mfma_f32_32x32x16_bf16 v[80:95], v[148:151], v[218:221], v[80:95]
	ds_read_b128 v[148:151], v173 offset:33024
	ds_read_b128 v[152:155], v173 offset:45312
	ds_read_b128 v[218:221], v181 offset:24576
	s_waitcnt lgkmcnt(0)
	v_mfma_f32_32x32x16_bf16 v[64:79], v[152:155], v[218:221], v[64:79]
	v_add_f32_e32 v154, 0, v130
	v_add_f32_e32 v154, v211, v154
	v_add_f32_e32 v154, v131, v154
	v_add_f32_e32 v154, v212, v154
	v_add_f32_e32 v154, v132, v154
	v_add_f32_e32 v154, v213, v154
	v_add_f32_e32 v154, v133, v154
	v_add_f32_e32 v154, v224, v154
	v_add_f32_e32 v154, v137, v154
	v_add_f32_e32 v154, v228, v154
	v_add_f32_e32 v154, v136, v154
	v_add_f32_e32 v154, v229, v154
	v_add_f32_e32 v154, v135, v154
	v_add_f32_e32 v154, v230, v154
	v_add_f32_e32 v154, v134, v154
	v_mfma_f32_32x32x16_bf16 v[80:95], v[148:151], v[218:221], v[80:95]
	ds_read_b64_tr_b16 v[232:233], v169 offset:0
	ds_read_b64_tr_b16 v[234:235], v169 offset:0x800
	ds_read_b64_tr_b16 v[236:237], v169 offset:0x1000
	ds_read_b64_tr_b16 v[238:239], v169 offset:0x1800
	ds_read_b64_tr_b16 v[240:241], v169 offset:0x2000
	ds_read_b64_tr_b16 v[242:243], v169 offset:0x2800
	ds_read_b64_tr_b16 v[244:245], v169 offset:0x3000
	ds_read_b64_tr_b16 v[246:247], v169 offset:0x3800
	v_exp_f32_e32 v148, v156
	v_add_f32_e32 v154, v231, v154
	v_add_f32_e32 v154, v145, v154
	v_exp_f32_e32 v149, v157
	v_add_f32_e32 v154, v147, v154
	v_add_f32_e32 v154, v144, v154
	v_exp_f32_e32 v150, v191
	v_add_f32_e32 v154, v148, v154
	v_add_f32_e32 v154, v143, v154
	v_exp_f32_e32 v151, v205
	v_add_f32_e32 v154, v149, v154
	v_add_f32_e32 v154, v140, v154
	v_exp_f32_e32 v152, v207
	v_add_f32_e32 v154, v150, v154
	v_add_f32_e32 v154, v139, v154
	v_exp_f32_e32 v153, v210
	v_add_f32_e32 v154, v151, v154
	v_add_f32_e32 v154, v146, v154
	v_add_f32_e32 v154, v152, v154
	v_add_f32_e32 v154, v142, v154
	v_add_f32_e32 v154, v153, v154
	v_add_f32_e32 v154, v141, v154
	v_add_f32_e32 v226, v138, v154
	v_mov_b32_e32 v227, v226
	v_cvt_pk_bf16_f32 v130, v130, v211
	v_cvt_pk_bf16_f32 v131, v131, v212
	v_cvt_pk_bf16_f32 v132, v132, v213
	s_nop 1
	v_permlane32_swap_b32_e32 v226, v227
	v_cvt_pk_bf16_f32 v133, v133, v224
	v_permlane32_swap_b32_e32 v130, v132
	v_cvt_pk_bf16_f32 v154, v137, v228
	v_cvt_pk_bf16_f32 v155, v136, v229
	v_cvt_pk_bf16_f32 v156, v135, v230
	v_cvt_pk_bf16_f32 v157, v134, v231
	v_cvt_pk_bf16_f32 v218, v145, v147
	v_cvt_pk_bf16_f32 v219, v144, v148
	v_cvt_pk_bf16_f32 v220, v143, v149
	v_cvt_pk_bf16_f32 v221, v140, v150
	v_cvt_pk_bf16_f32 v228, v139, v151
	v_cvt_pk_bf16_f32 v229, v146, v152
	v_cvt_pk_bf16_f32 v230, v142, v153
	v_cvt_pk_bf16_f32 v231, v141, v138
	v_permlane32_swap_b32_e32 v131, v133
	v_permlane32_swap_b32_e32 v154, v156
	v_permlane32_swap_b32_e32 v155, v157
	v_permlane32_swap_b32_e32 v218, v220
	v_permlane32_swap_b32_e32 v219, v221
	v_permlane32_swap_b32_e32 v228, v230
	v_permlane32_swap_b32_e32 v229, v231
	s_add_i32 s38, s69, 1
	s_cmp_lt_u32 s38, s68
	s_cselect_b32 s14, 0, s68
	s_cselect_b32 s15, s25, s28
	s_lshl_b32 s14, s14, 6
	s_sub_i32 s14, s15, s14
	s_add_i32 s14, s37, s14
	s_add_i32 s14, s14, 64
	s_ashr_i32 s15, s14, 31
	v_lshl_add_u64 v[134:135], s[14:15], 0, v[174:175]
	v_lshl_add_u64 v[136:137], v[176:177], 0, s[14:15]
	v_lshlrev_b64 v[134:135], 12, v[134:135]
	v_lshlrev_b64 v[136:137], 12, v[136:137]
	v_lshl_add_u64 v[134:135], v[178:179], 0, v[134:135]
	v_lshl_add_u64 v[138:139], v[178:179], 0, v[136:137]
	v_mad_i64_i32 v[142:143], s[20:21], v164, s14, 0
	v_mad_i64_i32 v[146:147], s[20:21], v168, s14, 0
	v_mad_i64_i32 v[150:151], s[14:15], v172, s14, 0
	global_load_dwordx4 v[134:137], v[134:135], off offset:256
	s_nop 0
	global_load_dwordx4 v[138:141], v[138:139], off offset:256
	v_lshl_add_u64 v[142:143], v[142:143], 1, v[162:163]
	v_lshl_add_u64 v[146:147], v[146:147], 1, v[166:167]
	v_lshl_add_u64 v[150:151], v[150:151], 1, v[170:171]
	global_load_dwordx4 v[142:145], v[142:143], off
	s_nop 0
	global_load_dwordx4 v[146:149], v[146:147], off
	s_nop 0
	global_load_dwordx4 v[150:153], v[150:151], off
	s_waitcnt lgkmcnt(0)
; #define SBAR() __builtin_amdgcn_sched_barrier(0)
; template <int OFF> __device__ __forceinline__ s16x4 tr_read(int vb) { s16x4 r; asm volatile("ds_read_b64_tr_b16 %0, %1 offset:%2" : "=&v"(r) : "v"(vb), "i"(OFF) : "memory"); return r; }
; template <int D0> __device__ __forceinline__ void pv_one(f32x16& od, int vb, bf16x8 pa0, bf16x8 pa1, bf16x8 pa2, bf16x8 pa3) {
;     const s16x4 l0 = tr_read<v_rd_off(D0, 0, 0)>(vb), h0 = tr_read<v_rd_off(D0, 0, 1)>(vb), l1 = tr_read<v_rd_off(D0, 1, 0)>(vb), h1 = tr_read<v_rd_off(D0, 1, 1)>(vb);
;     const s16x4 l2 = tr_read<v_rd_off(D0, 2, 0)>(vb), h2 = tr_read<v_rd_off(D0, 2, 1)>(vb), l3 = tr_read<v_rd_off(D0, 3, 0)>(vb), h3 = tr_read<v_rd_off(D0, 3, 1)>(vb);
;     asm volatile("s_waitcnt lgkmcnt(0)" ::: "memory"); SBAR();
;     ...
;     od = __builtin_amdgcn_mfma_f32_32x32x16_bf16(pa0, PK(l0, h0), od, 0, 0, 0);
;     od = __builtin_amdgcn_mfma_f32_32x32x16_bf16(pa1, PK(l1, h1), od, 0, 0, 0);
;     od = __builtin_amdgcn_mfma_f32_32x32x16_bf16(pa2, PK(l2, h2), od, 0, 0, 0);
;     od = __builtin_amdgcn_mfma_f32_32x32x16_bf16(pa3, PK(l3, h3), od, 0, 0, 0);
;     ...
; }
; __device__ __forceinline__ void pv_d0(f32x16* o, int vb, bf16x8 pa0, bf16x8 pa1, bf16x8 pa2, bf16x8 pa3) {
;     pv_one<0>(o[0], vb, pa0, pa1, pa2, pa3); pv_one<1>(o[1], vb, pa0, pa1, pa2, pa3); pv_one<2>(o[2], vb, pa0, pa1, pa2, pa3); pv_one<3>(o[3], vb, pa0, pa1, pa2, pa3);
; }
; __device__ __forceinline__ void partialSM(f32x16& p0, f32x16& p1, float& m_reg, float& mn, float& alpha, const float C, const float thr) {
;     float pmax = p0[0];
; #pragma unroll
;     for (int r = 1; r < 16; ++r) pmax = fmaxf(pmax, p0[r]);
; #pragma unroll
;     for (int r = 0; r < 16; ++r) pmax = fmaxf(pmax, p1[r]);
;     { auto rr = __builtin_amdgcn_permlane32_swap(__float_as_uint(pmax), __float_as_uint(pmax), false, false);
;       pmax = fmaxf(__uint_as_float(rr[0]), __uint_as_float(rr[1])); }
;     if (__builtin_expect(__all(pmax - m_reg <= thr), 1)) { mn = m_reg; alpha = 1.f; }
;     else { mn = fmaxf(m_reg, pmax); alpha = __builtin_amdgcn_exp2f((m_reg - mn) * C); m_reg = mn; }
;     const float mnC = -mn * C;
; #pragma unroll
;     for (int r = 0; r < 16; ++r) p0[r] = fmaf(p0[r], C, mnC);
; #pragma unroll
;     for (int r = 0; r < 16; ++r) p1[r] = fmaf(p1[r], C, mnC);
; #pragma unroll
;     for (int r = 0; r < 16; ++r) p0[r] = __builtin_amdgcn_exp2f(p0[r]);
; }
	s_nop 0
	v_mfma_f32_32x32x16_bf16 v[48:63], v[130:133], v[232:235], v[48:63]
	ds_read_b64_tr_b16 v[232:233], v169 offset:0x200
	ds_read_b64_tr_b16 v[234:235], v169 offset:0xa00
	v_mfma_f32_32x32x16_bf16 v[48:63], v[154:157], v[236:239], v[48:63]
	ds_read_b64_tr_b16 v[236:237], v169 offset:0x1200
	ds_read_b64_tr_b16 v[238:239], v169 offset:0x1a00
	v_mfma_f32_32x32x16_bf16 v[48:63], v[218:221], v[240:243], v[48:63]
	ds_read_b64_tr_b16 v[240:241], v169 offset:0x2200
	ds_read_b64_tr_b16 v[242:243], v169 offset:0x2a00
	v_mfma_f32_32x32x16_bf16 v[48:63], v[228:231], v[244:247], v[48:63]
	ds_read_b64_tr_b16 v[244:245], v169 offset:0x3200
	ds_read_b64_tr_b16 v[246:247], v169 offset:0x3a00
	s_waitcnt lgkmcnt(0)
	v_mfma_f32_32x32x16_bf16 v[32:47], v[130:133], v[232:235], v[32:47]
	ds_read_b64_tr_b16 v[232:233], v169 offset:0x400
	ds_read_b64_tr_b16 v[234:235], v169 offset:0xc00
	v_mfma_f32_32x32x16_bf16 v[32:47], v[154:157], v[236:239], v[32:47]
	ds_read_b64_tr_b16 v[236:237], v169 offset:0x1400
	ds_read_b64_tr_b16 v[238:239], v169 offset:0x1c00
	v_mfma_f32_32x32x16_bf16 v[32:47], v[218:221], v[240:243], v[32:47]
	ds_read_b64_tr_b16 v[240:241], v169 offset:0x2400
	ds_read_b64_tr_b16 v[242:243], v169 offset:0x2c00
	v_mfma_f32_32x32x16_bf16 v[32:47], v[228:231], v[244:247], v[32:47]
	ds_read_b64_tr_b16 v[244:245], v169 offset:0x3400
	ds_read_b64_tr_b16 v[246:247], v169 offset:0x3c00
	s_waitcnt lgkmcnt(0)
	v_mfma_f32_32x32x16_bf16 v[16:31], v[130:133], v[232:235], v[16:31]
	ds_read_b64_tr_b16 v[232:233], v169 offset:0x600
	ds_read_b64_tr_b16 v[234:235], v169 offset:0xe00
	v_mfma_f32_32x32x16_bf16 v[16:31], v[154:157], v[236:239], v[16:31]
	ds_read_b64_tr_b16 v[236:237], v169 offset:0x1600
	ds_read_b64_tr_b16 v[238:239], v169 offset:0x1e00
	v_mfma_f32_32x32x16_bf16 v[16:31], v[218:221], v[240:243], v[16:31]
	ds_read_b64_tr_b16 v[240:241], v169 offset:0x2600
	ds_read_b64_tr_b16 v[242:243], v169 offset:0x2e00
	v_mfma_f32_32x32x16_bf16 v[16:31], v[228:231], v[244:247], v[16:31]
	ds_read_b64_tr_b16 v[244:245], v169 offset:0x3600
	ds_read_b64_tr_b16 v[246:247], v169 offset:0x3e00
	s_waitcnt lgkmcnt(0)
	v_mfma_f32_32x32x16_bf16 v[0:15], v[130:133], v[232:235], v[0:15]
	v_max_f32_e32 v130, v81, v81
	v_max_f32_e32 v131, v80, v80
	v_max_f32_e32 v130, v131, v130
	v_max3_f32 v130, v130, v82, v83
	v_max3_f32 v130, v130, v84, v85
	v_max3_f32 v130, v130, v86, v87
	v_max3_f32 v130, v130, v88, v89
	v_max3_f32 v130, v130, v90, v91
	v_max3_f32 v130, v130, v92, v93
	v_mfma_f32_32x32x16_bf16 v[0:15], v[154:157], v[236:239], v[0:15]
	v_max3_f32 v130, v130, v94, v95
	v_max3_f32 v130, v130, v64, v65
	v_max3_f32 v130, v130, v66, v67
	v_max3_f32 v130, v130, v68, v69
	v_max3_f32 v130, v130, v70, v71
	v_max3_f32 v130, v130, v72, v73
	v_max3_f32 v130, v130, v74, v75
	v_max3_f32 v130, v130, v76, v77
	v_mfma_f32_32x32x16_bf16 v[0:15], v[218:221], v[240:243], v[0:15]
	v_max3_f32 v130, v130, v78, v79
	v_mov_b32_e32 v131, v130
	s_nop 1
	v_permlane32_swap_b32_e32 v130, v131
	v_max_f32_e32 v131, v131, v131
	v_max_f32_e32 v130, v130, v130
	v_max_f32_e32 v130, v130, v131
	v_sub_f32_e32 v131, v130, v204
	v_cmp_ge_f32_e32 vcc, s72, v131
	v_max_f32_e32 v131, v204, v204
	v_max_f32_e32 v130, v131, v130
	v_mfma_f32_32x32x16_bf16 v[0:15], v[228:231], v[244:247], v[0:15]
	v_sub_f32_e32 v131, v204, v130
	v_mul_f32_e32 v131, 0x3dd53b94, v131
	v_exp_f32_e32 v131, v131
	s_cmp_eq_u64 vcc, exec
	s_cselect_b64 s[14:15], -1, 0
	v_cndmask_b32_e64 v224, v131, 1.0, s[14:15]
	v_cmp_gt_f32_e32 vcc, 1.0, v224
	s_barrier
	s_waitcnt vmcnt(4)
	ds_write_b128 v186, v[134:137] offset:16384
	s_waitcnt vmcnt(3)
	ds_write_b128 v188, v[138:141] offset:16384
	s_waitcnt vmcnt(2)
	ds_write_b128 v194, v[142:145] offset:57344
	s_waitcnt vmcnt(1)
	ds_write_b128 v196, v[146:149] offset:57344
	s_waitcnt vmcnt(0)
	ds_write_b128 v198, v[150:153] offset:57344
	s_cbranch_vccz .LBB0_227
	s_and_saveexec_b64 s[20:21], s[12:13]
	ds_write_b32 v165, v224 offset:128
	s_or_b64 exec, exec, s[20:21]
	s_waitcnt lgkmcnt(0)
	v_add_u32_e32 v131, v161, v96
	ds_read_b128 v[132:135], v131 offset:224
	ds_read_b128 v[136:139], v131 offset:192
	ds_read_b128 v[140:143], v131 offset:160
	ds_read_b128 v[144:147], v131 offset:128
	s_waitcnt lgkmcnt(3)
	v_pk_mul_f32 v[60:61], v[60:61], v[132:133]
	s_waitcnt lgkmcnt(2)
	v_pk_mul_f32 v[56:57], v[56:57], v[136:137]
	s_waitcnt lgkmcnt(1)
	v_pk_mul_f32 v[52:53], v[52:53], v[140:141]
	v_pk_mul_f32 v[62:63], v[62:63], v[134:135]
	v_pk_mul_f32 v[58:59], v[58:59], v[138:139]
	v_pk_mul_f32 v[54:55], v[54:55], v[142:143]
	s_waitcnt lgkmcnt(0)
	v_pk_mul_f32 v[50:51], v[50:51], v[146:147]
	v_pk_mul_f32 v[48:49], v[48:49], v[144:145]
	v_pk_mul_f32 v[44:45], v[44:45], v[132:133]
	v_pk_mul_f32 v[40:41], v[40:41], v[136:137]
	v_pk_mul_f32 v[36:37], v[36:37], v[140:141]
	v_pk_mul_f32 v[46:47], v[46:47], v[134:135]
	v_pk_mul_f32 v[42:43], v[42:43], v[138:139]
	v_pk_mul_f32 v[38:39], v[38:39], v[142:143]
	v_pk_mul_f32 v[34:35], v[34:35], v[146:147]
	v_pk_mul_f32 v[32:33], v[32:33], v[144:145]
	v_pk_mul_f32 v[28:29], v[28:29], v[132:133]
	v_pk_mul_f32 v[24:25], v[24:25], v[136:137]
	v_pk_mul_f32 v[20:21], v[20:21], v[140:141]
	v_pk_mul_f32 v[30:31], v[30:31], v[134:135]
	v_pk_mul_f32 v[26:27], v[26:27], v[138:139]
	v_pk_mul_f32 v[22:23], v[22:23], v[142:143]
	v_pk_mul_f32 v[18:19], v[18:19], v[146:147]
	v_pk_mul_f32 v[16:17], v[16:17], v[144:145]
	v_pk_mul_f32 v[12:13], v[12:13], v[132:133]
	v_pk_mul_f32 v[8:9], v[8:9], v[136:137]
	v_pk_mul_f32 v[4:5], v[4:5], v[140:141]
	v_pk_mul_f32 v[14:15], v[14:15], v[134:135]
	v_pk_mul_f32 v[10:11], v[10:11], v[138:139]
	v_pk_mul_f32 v[6:7], v[6:7], v[142:143]
	v_pk_mul_f32 v[2:3], v[2:3], v[146:147]
	v_pk_mul_f32 v[0:1], v[0:1], v[144:145]
